# static priority raise for waves 4-7 inside the attention loops
# baseline (speedup 1.0000x reference)
.LBB0_1057:
	s_or_b64 exec, exec, s[4:5]
	s_waitcnt lgkmcnt(0)
	v_add_u32_e32 v72, v176, v178
	ds_read_b128 v[64:67], v72
	ds_read_b128 v[68:71], v72 offset:32
	s_add_i32 s37, s37, s25
	v_readlane_b32 s4, v254, 13
	v_readlane_b32 s5, v254, 14
	s_waitcnt lgkmcnt(1)
	v_rcp_f32_e32 v73, v64
	v_rcp_f32_e32 v74, v65
	v_rcp_f32_e32 v75, v66
	v_rcp_f32_e32 v76, v67
	ds_read_b128 v[64:67], v72 offset:64
	s_add_u32 s6, s4, s51
	s_addc_u32 s7, s5, s37
	s_lshl_b64 s[4:5], s[90:91], 2
	s_add_u32 s4, s6, s4
	s_addc_u32 s5, s7, s5
	s_waitcnt lgkmcnt(1)
	v_rcp_f32_e32 v77, v68
	v_rcp_f32_e32 v78, v69
	v_rcp_f32_e32 v79, v70
	v_rcp_f32_e32 v80, v71
	ds_read_b128 v[68:71], v72 offset:96
	s_waitcnt lgkmcnt(1)
	v_rcp_f32_e32 v72, v64
	v_rcp_f32_e32 v81, v65
	v_mov_b64_e32 v[64:65], s[4:5]
	s_movk_i32 s4, 0xc00
	v_mad_i64_i32 v[64:65], s[4:5], v185, s4, v[64:65]
	v_lshlrev_b32_e32 v176, 2, v184
	v_lshl_add_u64 v[64:65], v[64:65], 0, v[176:177]
	v_mul_u32_u24_e32 v176, 0x3000, v183
	v_lshl_add_u64 v[64:65], v[64:65], 0, v[176:177]
	v_mul_f32_e32 v0, v0, v73
	global_store_dword v[64:65], v0, off
	v_mul_f32_e32 v0, v48, v73
	global_store_dword v[64:65], v0, off offset:128
	v_mul_f32_e32 v0, v32, v73
	global_store_dword v[64:65], v0, off offset:256
	v_mul_f32_e32 v0, v16, v73
	global_store_dword v[64:65], v0, off offset:384
	v_mul_f32_e32 v0, v1, v74
	global_store_dword v[64:65], v0, off offset:3072
	v_mul_f32_e32 v0, v49, v74
	global_store_dword v[64:65], v0, off offset:3200
	v_mul_f32_e32 v0, v33, v74
	global_store_dword v[64:65], v0, off offset:3328
	v_mul_f32_e32 v0, v17, v74
	global_store_dword v[64:65], v0, off offset:3456
	v_add_co_u32_e32 v0, vcc, s30, v64
	v_mul_f32_e32 v2, v2, v75
	s_nop 0
	v_addc_co_u32_e32 v1, vcc, 0, v65, vcc
	global_store_dword v[0:1], v2, off offset:2048
	v_mul_f32_e32 v2, v50, v75
	global_store_dword v[0:1], v2, off offset:2176
	v_mul_f32_e32 v2, v34, v75
	global_store_dword v[0:1], v2, off offset:2304
	v_mul_f32_e32 v2, v18, v75
	global_store_dword v[0:1], v2, off offset:2432
	v_add_co_u32_e32 v0, vcc, s45, v64
	v_mul_f32_e32 v2, v3, v76
	s_nop 0
	v_addc_co_u32_e32 v1, vcc, 0, v65, vcc
	global_store_dword v[0:1], v2, off offset:1024
	v_mul_f32_e32 v2, v51, v76
	global_store_dword v[0:1], v2, off offset:1152
	v_mul_f32_e32 v2, v35, v76
	global_store_dword v[0:1], v2, off offset:1280
	v_mul_f32_e32 v2, v19, v76
	s_movk_i32 s4, 0x6000
	global_store_dword v[0:1], v2, off offset:1408
	v_add_co_u32_e32 v0, vcc, s4, v64
	v_mul_f32_e32 v2, v4, v77
	s_nop 0
	v_addc_co_u32_e32 v1, vcc, 0, v65, vcc
	global_store_dword v[0:1], v2, off
	v_mul_f32_e32 v2, v52, v77
	global_store_dword v[0:1], v2, off offset:128
	v_mul_f32_e32 v2, v36, v77
	global_store_dword v[0:1], v2, off offset:256
	v_mul_f32_e32 v2, v20, v77
	global_store_dword v[0:1], v2, off offset:384
	v_mul_f32_e32 v2, v5, v78
	global_store_dword v[0:1], v2, off offset:3072
	v_mul_f32_e32 v2, v53, v78
	global_store_dword v[0:1], v2, off offset:3200
	v_mul_f32_e32 v2, v37, v78
	global_store_dword v[0:1], v2, off offset:3328
	v_mul_f32_e32 v2, v21, v78
	s_movk_i32 s4, 0x7000
	global_store_dword v[0:1], v2, off offset:3456
	v_add_co_u32_e32 v0, vcc, s4, v64
	v_mul_f32_e32 v2, v6, v79
	s_nop 0
	v_addc_co_u32_e32 v1, vcc, 0, v65, vcc
	global_store_dword v[0:1], v2, off offset:2048
	v_mul_f32_e32 v2, v54, v79
	global_store_dword v[0:1], v2, off offset:2176
	v_mul_f32_e32 v2, v38, v79
	global_store_dword v[0:1], v2, off offset:2304
	v_mul_f32_e32 v2, v22, v79
	s_mov_b32 s4, 0x8000
	global_store_dword v[0:1], v2, off offset:2432
	v_add_co_u32_e32 v0, vcc, s4, v64
	v_mul_f32_e32 v2, v7, v80
	s_nop 0
	v_addc_co_u32_e32 v1, vcc, 0, v65, vcc
	global_store_dword v[0:1], v2, off offset:1024
	v_mul_f32_e32 v2, v55, v80
	global_store_dword v[0:1], v2, off offset:1152
	v_mul_f32_e32 v2, v39, v80
	global_store_dword v[0:1], v2, off offset:1280
	v_mul_f32_e32 v2, v23, v80
	s_mov_b32 s4, 0xc000
	global_store_dword v[0:1], v2, off offset:1408
	v_add_co_u32_e32 v0, vcc, s4, v64
	v_mul_f32_e32 v2, v8, v72
	s_nop 0
	v_addc_co_u32_e32 v1, vcc, 0, v65, vcc
	global_store_dword v[0:1], v2, off
	v_mul_f32_e32 v2, v56, v72
	global_store_dword v[0:1], v2, off offset:128
	v_mul_f32_e32 v2, v40, v72
	global_store_dword v[0:1], v2, off offset:256
	v_mul_f32_e32 v2, v24, v72
	global_store_dword v[0:1], v2, off offset:384
	v_mul_f32_e32 v2, v9, v81
	v_rcp_f32_e32 v66, v66
	global_store_dword v[0:1], v2, off offset:3072
	v_mul_f32_e32 v2, v57, v81
	global_store_dword v[0:1], v2, off offset:3200
	v_mul_f32_e32 v2, v41, v81
	global_store_dword v[0:1], v2, off offset:3328
	v_mul_f32_e32 v2, v25, v81
	s_mov_b32 s4, 0xd000
	global_store_dword v[0:1], v2, off offset:3456
	v_add_co_u32_e32 v0, vcc, s4, v64
	v_mul_f32_e32 v2, v10, v66
	s_nop 0
	v_addc_co_u32_e32 v1, vcc, 0, v65, vcc
	v_rcp_f32_e32 v67, v67
	global_store_dword v[0:1], v2, off offset:2048
	v_mul_f32_e32 v2, v58, v66
	global_store_dword v[0:1], v2, off offset:2176
	v_mul_f32_e32 v2, v42, v66
	global_store_dword v[0:1], v2, off offset:2304
	v_mul_f32_e32 v2, v26, v66
	s_mov_b32 s4, 0xe000
	global_store_dword v[0:1], v2, off offset:2432
	v_add_co_u32_e32 v0, vcc, s4, v64
	v_mul_f32_e32 v2, v11, v67
	s_nop 0
	v_addc_co_u32_e32 v1, vcc, 0, v65, vcc
	s_waitcnt lgkmcnt(0)
	v_rcp_f32_e32 v68, v68
	global_store_dword v[0:1], v2, off offset:1024
	v_mul_f32_e32 v2, v59, v67
	global_store_dword v[0:1], v2, off offset:1152
	v_mul_f32_e32 v2, v43, v67
	global_store_dword v[0:1], v2, off offset:1280
	v_mul_f32_e32 v2, v27, v67
	s_mov_b32 s4, 0x12000
	global_store_dword v[0:1], v2, off offset:1408
	v_add_co_u32_e32 v0, vcc, s4, v64
	v_rcp_f32_e32 v69, v69
	v_mul_f32_e32 v2, v12, v68
	v_addc_co_u32_e32 v1, vcc, 0, v65, vcc
	global_store_dword v[0:1], v2, off
	v_mul_f32_e32 v2, v60, v68
	global_store_dword v[0:1], v2, off offset:128
	v_mul_f32_e32 v2, v44, v68
	global_store_dword v[0:1], v2, off offset:256
	v_mul_f32_e32 v2, v28, v68
	global_store_dword v[0:1], v2, off offset:384
	v_mul_f32_e32 v2, v13, v69
	v_rcp_f32_e32 v70, v70
	global_store_dword v[0:1], v2, off offset:3072
	v_mul_f32_e32 v2, v61, v69
	global_store_dword v[0:1], v2, off offset:3200
	v_mul_f32_e32 v2, v45, v69
	global_store_dword v[0:1], v2, off offset:3328
	v_mul_f32_e32 v2, v29, v69
	global_store_dword v[0:1], v2, off offset:3456
	v_add_co_u32_e32 v0, vcc, 0x13000, v64
	v_mul_f32_e32 v2, v14, v70
	s_nop 0
	v_addc_co_u32_e32 v1, vcc, 0, v65, vcc
	v_rcp_f32_e32 v71, v71
	global_store_dword v[0:1], v2, off offset:2048
	v_mul_f32_e32 v2, v62, v70
	global_store_dword v[0:1], v2, off offset:2176
	v_mul_f32_e32 v2, v46, v70
	global_store_dword v[0:1], v2, off offset:2304
	v_mul_f32_e32 v2, v30, v70
	global_store_dword v[0:1], v2, off offset:2432
	v_add_co_u32_e32 v0, vcc, 0x14000, v64
	v_mul_f32_e32 v2, v15, v71
	s_nop 0
	v_addc_co_u32_e32 v1, vcc, 0, v65, vcc
	global_store_dword v[0:1], v2, off offset:1024
	v_mul_f32_e32 v2, v63, v71
	global_store_dword v[0:1], v2, off offset:1152
	v_mul_f32_e32 v2, v47, v71
	global_store_dword v[0:1], v2, off offset:1280
	v_mul_f32_e32 v2, v31, v71
	global_store_dword v[0:1], v2, off offset:1408
	s_waitcnt vmcnt(63) expcnt(7) lgkmcnt(15)
	s_setprio 0
	s_barrier

.LBB0_1085:
	v_readfirstlane_b32 s100, v214
	s_bitcmp1_b32 s100, 8
	s_cbranch_scc0 .Lprio_1
	s_setprio 1

.LBB0_1101:
	v_cndmask_b32_e64 v99, v99, v140, s[4:5]
	v_mul_f32_e32 v99, 0xbe38aa3b, v99
	v_fmamk_f32 v80, v80, 0x3e38aa3b, v99
	v_fmamk_f32 v81, v81, 0x3e38aa3b, v99
	v_fmamk_f32 v108, v93, 0x3e38aa3b, v99
	v_fmamk_f32 v93, v74, 0x3e38aa3b, v99
	v_exp_f32_e32 v74, v80
	v_fmamk_f32 v82, v82, 0x3e38aa3b, v99
	v_fmamk_f32 v109, v94, 0x3e38aa3b, v99
	v_fmamk_f32 v94, v75, 0x3e38aa3b, v99
	v_exp_f32_e32 v75, v81
	v_fmamk_f32 v83, v83, 0x3e38aa3b, v99
	v_fmamk_f32 v110, v95, 0x3e38aa3b, v99
	v_fmamk_f32 v95, v76, 0x3e38aa3b, v99
	v_exp_f32_e32 v76, v82
	v_fmamk_f32 v84, v84, 0x3e38aa3b, v99
	v_fmamk_f32 v64, v64, 0x3e38aa3b, v99
	v_exp_f32_e32 v80, v83
	v_fmamk_f32 v100, v85, 0x3e38aa3b, v99
	v_fmamk_f32 v101, v86, 0x3e38aa3b, v99
	v_fmamk_f32 v102, v87, 0x3e38aa3b, v99
	v_fmamk_f32 v103, v88, 0x3e38aa3b, v99
	v_fmamk_f32 v104, v89, 0x3e38aa3b, v99
	v_fmamk_f32 v105, v90, 0x3e38aa3b, v99
	v_fmamk_f32 v106, v91, 0x3e38aa3b, v99
	v_fmamk_f32 v107, v92, 0x3e38aa3b, v99
	v_fmamk_f32 v65, v65, 0x3e38aa3b, v99
	v_fmamk_f32 v85, v66, 0x3e38aa3b, v99
	v_fmamk_f32 v86, v67, 0x3e38aa3b, v99
	v_fmamk_f32 v87, v68, 0x3e38aa3b, v99
	v_fmamk_f32 v88, v69, 0x3e38aa3b, v99
	v_fmamk_f32 v89, v70, 0x3e38aa3b, v99
	v_fmamk_f32 v90, v71, 0x3e38aa3b, v99
	v_fmamk_f32 v91, v72, 0x3e38aa3b, v99
	v_fmamk_f32 v92, v73, 0x3e38aa3b, v99
	v_exp_f32_e32 v81, v84
	v_fmamk_f32 v77, v77, 0x3e38aa3b, v99
	v_fmamk_f32 v78, v78, 0x3e38aa3b, v99
	v_fmac_f32_e32 v99, 0x3e38aa3b, v79
	v_exp_f32_e32 v79, v64
	v_add_f32_e32 v64, 0, v74
	v_exp_f32_e32 v82, v100
	v_add_f32_e32 v64, v75, v64
	v_exp_f32_e32 v83, v101
	v_add_f32_e32 v64, v76, v64
	v_exp_f32_e32 v84, v102
	v_add_f32_e32 v64, v80, v64
	v_exp_f32_e32 v66, v103
	v_add_f32_e32 v64, v81, v64
	v_exp_f32_e32 v67, v104
	v_add_f32_e32 v64, v82, v64
	v_exp_f32_e32 v68, v105
	v_add_f32_e32 v64, v83, v64
	v_exp_f32_e32 v69, v106
	v_add_f32_e32 v64, v84, v64
	v_exp_f32_e32 v70, v107
	v_add_f32_e32 v64, v66, v64
	v_exp_f32_e32 v71, v108
	v_add_f32_e32 v64, v67, v64
	v_exp_f32_e32 v72, v109
	v_add_f32_e32 v64, v68, v64
	v_exp_f32_e32 v73, v110
	v_add_f32_e32 v64, v69, v64
	v_add_f32_e32 v64, v70, v64
	v_exp_f32_e32 v100, v65
	v_add_f32_e32 v64, v71, v64
	v_exp_f32_e32 v85, v85
	v_add_f32_e32 v64, v72, v64
	v_exp_f32_e32 v86, v86
	v_add_f32_e32 v64, v73, v64
	v_exp_f32_e32 v87, v87
	v_add_f32_e32 v64, v79, v64
	v_exp_f32_e32 v88, v88
	v_add_f32_e32 v64, v100, v64
	v_exp_f32_e32 v89, v89
	v_add_f32_e32 v64, v85, v64
	v_exp_f32_e32 v90, v90
	v_add_f32_e32 v64, v86, v64
	v_exp_f32_e32 v91, v91
	v_add_f32_e32 v64, v87, v64
	v_exp_f32_e32 v92, v92
	v_add_f32_e32 v64, v88, v64
	v_exp_f32_e32 v93, v93
	v_add_f32_e32 v64, v89, v64
	v_exp_f32_e32 v94, v94
	v_add_f32_e32 v64, v90, v64
	v_exp_f32_e32 v95, v95
	v_add_f32_e32 v64, v91, v64
	v_exp_f32_e32 v101, v77
	v_add_f32_e32 v64, v92, v64
	v_exp_f32_e32 v102, v78
	v_add_f32_e32 v64, v93, v64
	v_exp_f32_e32 v99, v99
	v_add_f32_e32 v64, v94, v64
	v_add_f32_e32 v64, v95, v64
	v_add_f32_e32 v64, v101, v64
	v_add_f32_e32 v64, v102, v64
	v_add_f32_e32 v64, v99, v64
	v_mov_b32_e32 v65, v64
	s_nop 1
	v_permlane32_swap_b32_e32 v64, v65
	v_cvt_pk_bf16_f32 v74, v74, v75
	v_cvt_pk_bf16_f32 v75, v76, v80
	v_cvt_pk_bf16_f32 v76, v81, v82
	v_cvt_pk_bf16_f32 v77, v83, v84
	v_cvt_pk_bf16_f32 v66, v66, v67
	v_cvt_pk_bf16_f32 v67, v68, v69
	v_cvt_pk_bf16_f32 v68, v70, v71
	v_cvt_pk_bf16_f32 v69, v72, v73
	v_cvt_pk_bf16_f32 v70, v79, v100
	v_cvt_pk_bf16_f32 v71, v85, v86
	v_cvt_pk_bf16_f32 v72, v87, v88
	v_cvt_pk_bf16_f32 v73, v89, v90
	v_cvt_pk_bf16_f32 v78, v91, v92
	v_cvt_pk_bf16_f32 v79, v93, v94
	v_cvt_pk_bf16_f32 v80, v95, v101
	v_cvt_pk_bf16_f32 v81, v102, v99
	v_permlane32_swap_b32_e32 v74, v76
	v_permlane32_swap_b32_e32 v75, v77
	v_permlane32_swap_b32_e32 v66, v68
	v_permlane32_swap_b32_e32 v67, v69
	v_permlane32_swap_b32_e32 v70, v72
	v_permlane32_swap_b32_e32 v71, v73
	v_permlane32_swap_b32_e32 v78, v80
	v_permlane32_swap_b32_e32 v79, v81
	ds_read_b64_tr_b16 v[82:83], v174 offset:0
	ds_read_b64_tr_b16 v[84:85], v174 offset:0x800
	ds_read_b64_tr_b16 v[86:87], v174 offset:0x1000
	ds_read_b64_tr_b16 v[88:89], v174 offset:0x1800
	ds_read_b64_tr_b16 v[90:91], v174 offset:0x2000
	ds_read_b64_tr_b16 v[92:93], v174 offset:0x2800
	ds_read_b64_tr_b16 v[100:101], v174 offset:0x3000
	ds_read_b64_tr_b16 v[102:103], v174 offset:0x3800
	s_waitcnt lgkmcnt(0)
	s_nop 0
	v_mfma_f32_32x32x16_bf16 v[0:15], v[74:77], v[82:85], v[0:15]
	ds_read_b64_tr_b16 v[82:83], v174 offset:0x200
	ds_read_b64_tr_b16 v[84:85], v174 offset:0xa00
	v_mfma_f32_32x32x16_bf16 v[0:15], v[66:69], v[86:89], v[0:15]
	ds_read_b64_tr_b16 v[86:87], v174 offset:0x1200
	ds_read_b64_tr_b16 v[88:89], v174 offset:0x1a00
	v_mfma_f32_32x32x16_bf16 v[0:15], v[70:73], v[90:93], v[0:15]
	ds_read_b64_tr_b16 v[90:91], v174 offset:0x2200
	ds_read_b64_tr_b16 v[92:93], v174 offset:0x2a00
	v_mfma_f32_32x32x16_bf16 v[0:15], v[78:81], v[100:103], v[0:15]
	ds_read_b64_tr_b16 v[100:101], v174 offset:0x3200
	ds_read_b64_tr_b16 v[102:103], v174 offset:0x3a00
	s_waitcnt lgkmcnt(0)
	v_mfma_f32_32x32x16_bf16 v[48:63], v[74:77], v[82:85], v[48:63]
	ds_read_b64_tr_b16 v[82:83], v174 offset:0x400
	ds_read_b64_tr_b16 v[84:85], v174 offset:0xc00
	v_mfma_f32_32x32x16_bf16 v[48:63], v[66:69], v[86:89], v[48:63]
	ds_read_b64_tr_b16 v[86:87], v174 offset:0x1400
	ds_read_b64_tr_b16 v[88:89], v174 offset:0x1c00
	v_mfma_f32_32x32x16_bf16 v[48:63], v[70:73], v[90:93], v[48:63]
	ds_read_b64_tr_b16 v[90:91], v174 offset:0x2400
	ds_read_b64_tr_b16 v[92:93], v174 offset:0x2c00
	v_mfma_f32_32x32x16_bf16 v[48:63], v[78:81], v[100:103], v[48:63]
	ds_read_b64_tr_b16 v[100:101], v174 offset:0x3400
	ds_read_b64_tr_b16 v[102:103], v174 offset:0x3c00
	s_waitcnt lgkmcnt(0)
	v_mfma_f32_32x32x16_bf16 v[32:47], v[74:77], v[82:85], v[32:47]
	ds_read_b64_tr_b16 v[82:83], v174 offset:0x600
	ds_read_b64_tr_b16 v[84:85], v174 offset:0xe00
	v_mfma_f32_32x32x16_bf16 v[32:47], v[66:69], v[86:89], v[32:47]
	ds_read_b64_tr_b16 v[86:87], v174 offset:0x1600
	ds_read_b64_tr_b16 v[88:89], v174 offset:0x1e00
	v_mfma_f32_32x32x16_bf16 v[32:47], v[70:73], v[90:93], v[32:47]
	ds_read_b64_tr_b16 v[90:91], v174 offset:0x2600
	ds_read_b64_tr_b16 v[92:93], v174 offset:0x2e00
	v_mfma_f32_32x32x16_bf16 v[32:47], v[78:81], v[100:103], v[32:47]
	ds_read_b64_tr_b16 v[100:101], v174 offset:0x3600
	ds_read_b64_tr_b16 v[102:103], v174 offset:0x3e00
	s_waitcnt lgkmcnt(0)
	v_mfma_f32_32x32x16_bf16 v[16:31], v[74:77], v[82:85], v[16:31]
	v_mfma_f32_32x32x16_bf16 v[16:31], v[66:69], v[86:89], v[16:31]
	v_mfma_f32_32x32x16_bf16 v[16:31], v[70:73], v[90:93], v[16:31]
	v_mfma_f32_32x32x16_bf16 v[16:31], v[78:81], v[100:103], v[16:31]
	s_and_saveexec_b64 s[4:5], s[6:7]
	v_add_f32_e32 v66, v96, v97
	v_fmac_f32_e32 v66, v173, v141
	v_add_f32_e32 v64, v64, v65
	v_fmac_f32_e32 v64, v66, v98
	ds_write_b32 v155, v64 offset:49152
	s_or_b64 exec, exec, s[4:5]
	s_waitcnt lgkmcnt(0)
	v_add_u32_e32 v72, v153, v178
	ds_read_b128 v[64:67], v72 offset:49152
	ds_read_b128 v[68:71], v72 offset:49184
	v_readlane_b32 s6, v253, 58
	v_readlane_b32 s8, v254, 11
	s_cmp_eq_u32 s28, 0
	v_readlane_b32 s7, v253, 59
	v_readlane_b32 s9, v254, 12
	s_cselect_b32 s4, s7, s9
	s_cselect_b32 s5, s6, s8
	s_add_i32 s6, s37, s25
	s_waitcnt lgkmcnt(1)
	v_rcp_f32_e32 v73, v64
	v_rcp_f32_e32 v74, v65
	v_rcp_f32_e32 v75, v66
	v_rcp_f32_e32 v76, v67
	ds_read_b128 v[64:67], v72 offset:49216
	s_add_u32 s7, s5, s51
	s_addc_u32 s6, s4, s6
	s_lshl_b64 s[4:5], s[90:91], 2
	s_add_u32 s4, s7, s4
	s_addc_u32 s5, s6, s5
	s_waitcnt lgkmcnt(1)
	v_rcp_f32_e32 v77, v68
	v_rcp_f32_e32 v78, v69
	v_rcp_f32_e32 v79, v70
	v_rcp_f32_e32 v80, v71
	ds_read_b128 v[68:71], v72 offset:49248
	s_waitcnt lgkmcnt(1)
	v_rcp_f32_e32 v72, v64
	v_rcp_f32_e32 v81, v65
	v_mov_b64_e32 v[64:65], s[4:5]
	s_movk_i32 s4, 0xc00
	v_mad_i64_i32 v[64:65], s[4:5], v185, s4, v[64:65]
	v_lshlrev_b32_e32 v176, 2, v184
	v_lshl_add_u64 v[64:65], v[64:65], 0, v[176:177]
	v_mul_u32_u24_e32 v176, 0x3000, v183
	v_lshl_add_u64 v[64:65], v[64:65], 0, v[176:177]
	v_mul_f32_e32 v0, v0, v73
	global_store_dword v[64:65], v0, off
	v_mul_f32_e32 v0, v48, v73
	global_store_dword v[64:65], v0, off offset:128
	v_mul_f32_e32 v0, v32, v73
	global_store_dword v[64:65], v0, off offset:256
	v_mul_f32_e32 v0, v16, v73
	global_store_dword v[64:65], v0, off offset:384
	v_mul_f32_e32 v0, v1, v74
	global_store_dword v[64:65], v0, off offset:3072
	v_mul_f32_e32 v0, v49, v74
	global_store_dword v[64:65], v0, off offset:3200
	v_mul_f32_e32 v0, v33, v74
	global_store_dword v[64:65], v0, off offset:3328
	v_mul_f32_e32 v0, v17, v74
	global_store_dword v[64:65], v0, off offset:3456
	v_add_co_u32_e32 v0, vcc, s48, v64
	v_mul_f32_e32 v2, v2, v75
	s_nop 0
	v_addc_co_u32_e32 v1, vcc, 0, v65, vcc
	global_store_dword v[0:1], v2, off offset:2048
	v_mul_f32_e32 v2, v50, v75
	global_store_dword v[0:1], v2, off offset:2176
	v_mul_f32_e32 v2, v34, v75
	global_store_dword v[0:1], v2, off offset:2304
	v_mul_f32_e32 v2, v18, v75
	global_store_dword v[0:1], v2, off offset:2432
	v_add_co_u32_e32 v0, vcc, s45, v64
	v_mul_f32_e32 v2, v3, v76
	s_nop 0
	v_addc_co_u32_e32 v1, vcc, 0, v65, vcc
	global_store_dword v[0:1], v2, off offset:1024
	v_mul_f32_e32 v2, v51, v76
	global_store_dword v[0:1], v2, off offset:1152
	v_mul_f32_e32 v2, v35, v76
	global_store_dword v[0:1], v2, off offset:1280
	v_mul_f32_e32 v2, v19, v76
	s_movk_i32 s4, 0x6000
	global_store_dword v[0:1], v2, off offset:1408
	v_add_co_u32_e32 v0, vcc, s4, v64
	v_mul_f32_e32 v2, v4, v77
	s_nop 0
	v_addc_co_u32_e32 v1, vcc, 0, v65, vcc
	global_store_dword v[0:1], v2, off
	v_mul_f32_e32 v2, v52, v77
	global_store_dword v[0:1], v2, off offset:128
	v_mul_f32_e32 v2, v36, v77
	global_store_dword v[0:1], v2, off offset:256
	v_mul_f32_e32 v2, v20, v77
	global_store_dword v[0:1], v2, off offset:384
	v_mul_f32_e32 v2, v5, v78
	global_store_dword v[0:1], v2, off offset:3072
	v_mul_f32_e32 v2, v53, v78
	global_store_dword v[0:1], v2, off offset:3200
	v_mul_f32_e32 v2, v37, v78
	global_store_dword v[0:1], v2, off offset:3328
	v_mul_f32_e32 v2, v21, v78
	s_movk_i32 s4, 0x7000
	global_store_dword v[0:1], v2, off offset:3456
	v_add_co_u32_e32 v0, vcc, s4, v64
	v_mul_f32_e32 v2, v6, v79
	s_nop 0
	v_addc_co_u32_e32 v1, vcc, 0, v65, vcc
	global_store_dword v[0:1], v2, off offset:2048
	v_mul_f32_e32 v2, v54, v79
	global_store_dword v[0:1], v2, off offset:2176
	v_mul_f32_e32 v2, v38, v79
	global_store_dword v[0:1], v2, off offset:2304
	v_mul_f32_e32 v2, v22, v79
	s_mov_b32 s4, 0x8000
	global_store_dword v[0:1], v2, off offset:2432
	v_add_co_u32_e32 v0, vcc, s4, v64
	v_mul_f32_e32 v2, v7, v80
	s_nop 0
	v_addc_co_u32_e32 v1, vcc, 0, v65, vcc
	global_store_dword v[0:1], v2, off offset:1024
	v_mul_f32_e32 v2, v55, v80
	global_store_dword v[0:1], v2, off offset:1152
	v_mul_f32_e32 v2, v39, v80
	global_store_dword v[0:1], v2, off offset:1280
	v_mul_f32_e32 v2, v23, v80
	s_mov_b32 s4, 0xc000
	global_store_dword v[0:1], v2, off offset:1408
	v_add_co_u32_e32 v0, vcc, s4, v64
	v_mul_f32_e32 v2, v8, v72
	s_nop 0
	v_addc_co_u32_e32 v1, vcc, 0, v65, vcc
	global_store_dword v[0:1], v2, off
	v_mul_f32_e32 v2, v56, v72
	global_store_dword v[0:1], v2, off offset:128
	v_mul_f32_e32 v2, v40, v72
	global_store_dword v[0:1], v2, off offset:256
	v_mul_f32_e32 v2, v24, v72
	global_store_dword v[0:1], v2, off offset:384
	v_mul_f32_e32 v2, v9, v81
	v_rcp_f32_e32 v66, v66
	global_store_dword v[0:1], v2, off offset:3072
	v_mul_f32_e32 v2, v57, v81
	global_store_dword v[0:1], v2, off offset:3200
	v_mul_f32_e32 v2, v41, v81
	global_store_dword v[0:1], v2, off offset:3328
	v_mul_f32_e32 v2, v25, v81
	s_mov_b32 s4, 0xd000
	global_store_dword v[0:1], v2, off offset:3456
	v_add_co_u32_e32 v0, vcc, s4, v64
	v_mul_f32_e32 v2, v10, v66
	s_nop 0
	v_addc_co_u32_e32 v1, vcc, 0, v65, vcc
	v_rcp_f32_e32 v67, v67
	global_store_dword v[0:1], v2, off offset:2048
	v_mul_f32_e32 v2, v58, v66
	global_store_dword v[0:1], v2, off offset:2176
	v_mul_f32_e32 v2, v42, v66
	global_store_dword v[0:1], v2, off offset:2304
	v_mul_f32_e32 v2, v26, v66
	s_mov_b32 s4, 0xe000
	global_store_dword v[0:1], v2, off offset:2432
	v_add_co_u32_e32 v0, vcc, s4, v64
	v_mul_f32_e32 v2, v11, v67
	s_nop 0
	v_addc_co_u32_e32 v1, vcc, 0, v65, vcc
	s_waitcnt lgkmcnt(0)
	v_rcp_f32_e32 v68, v68
	global_store_dword v[0:1], v2, off offset:1024
	v_mul_f32_e32 v2, v59, v67
	global_store_dword v[0:1], v2, off offset:1152
	v_mul_f32_e32 v2, v43, v67
	global_store_dword v[0:1], v2, off offset:1280
	v_mul_f32_e32 v2, v27, v67
	s_mov_b32 s4, 0x12000
	global_store_dword v[0:1], v2, off offset:1408
	v_add_co_u32_e32 v0, vcc, s4, v64
	v_rcp_f32_e32 v69, v69
	v_mul_f32_e32 v2, v12, v68
	v_addc_co_u32_e32 v1, vcc, 0, v65, vcc
	global_store_dword v[0:1], v2, off
	v_mul_f32_e32 v2, v60, v68
	global_store_dword v[0:1], v2, off offset:128
	v_mul_f32_e32 v2, v44, v68
	global_store_dword v[0:1], v2, off offset:256
	v_mul_f32_e32 v2, v28, v68
	global_store_dword v[0:1], v2, off offset:384
	v_mul_f32_e32 v2, v13, v69
	v_rcp_f32_e32 v70, v70
	global_store_dword v[0:1], v2, off offset:3072
	v_mul_f32_e32 v2, v61, v69
	global_store_dword v[0:1], v2, off offset:3200
	v_mul_f32_e32 v2, v45, v69
	global_store_dword v[0:1], v2, off offset:3328
	v_mul_f32_e32 v2, v29, v69
	s_mov_b32 s4, 0x13000
	global_store_dword v[0:1], v2, off offset:3456
	v_add_co_u32_e32 v0, vcc, s4, v64
	v_mul_f32_e32 v2, v14, v70
	s_nop 0
	v_addc_co_u32_e32 v1, vcc, 0, v65, vcc
	v_rcp_f32_e32 v71, v71
	global_store_dword v[0:1], v2, off offset:2048
	v_mul_f32_e32 v2, v62, v70
	global_store_dword v[0:1], v2, off offset:2176
	v_mul_f32_e32 v2, v46, v70
	global_store_dword v[0:1], v2, off offset:2304
	v_mul_f32_e32 v2, v30, v70
	s_mov_b32 s4, 0x14000
	global_store_dword v[0:1], v2, off offset:2432
	v_add_co_u32_e32 v0, vcc, s4, v64
	v_mul_f32_e32 v2, v15, v71
	s_nop 0
	v_addc_co_u32_e32 v1, vcc, 0, v65, vcc
	global_store_dword v[0:1], v2, off offset:1024
	v_mul_f32_e32 v2, v63, v71
	global_store_dword v[0:1], v2, off offset:1152
	v_mul_f32_e32 v2, v47, v71
	global_store_dword v[0:1], v2, off offset:1280
	v_mul_f32_e32 v2, v31, v71
	s_mov_b64 s[8:9], 0
	global_store_dword v[0:1], v2, off offset:1408
	s_waitcnt vmcnt(63) expcnt(7) lgkmcnt(15)
	s_setprio 0
	s_barrier
